# code placement: the six GEMM main-loop heads aligned to 64 B (.p2align 6), on v064
# speedup vs baseline: 1.0020x; 1.0020x over previous
.LBB0_586:
	s_xor_b64 s[46:47], s[64:65], -1
	s_add_u32 s21, s30, 0x100
	s_addc_u32 s74, s31, 0
	s_ashr_i32 s45, s44, 31
	s_lshl_b64 s[16:17], s[44:45], 20
	s_add_u32 s38, s54, s16
	s_addc_u32 s39, s55, s17
	s_and_b64 s[16:17], s[64:65], exec
	s_cselect_b32 s61, s39, s53
	s_cselect_b32 s60, s38, s52
	s_ashr_i32 s51, s50, 31
	s_lshl_b64 s[16:17], s[50:51], 20
	s_add_u32 s38, s56, s16
	s_addc_u32 s39, s57, s17
	s_and_b64 s[16:17], s[64:65], exec
	s_cselect_b32 s31, s39, s31
	s_cselect_b32 s30, s38, s30
	s_add_u32 s16, s52, 0x80080
	s_addc_u32 s17, s53, 0
	v_lshl_add_u64 v[134:135], s[16:17], 0, v[148:149]
	v_lshl_add_u64 v[136:137], s[16:17], 0, v[150:151]
	s_mov_b32 s40, -2
	.p2align	6

.LBB0_727:
	s_add_u32 s41, s16, 0x100
	s_addc_u32 s10, s17, 0
	s_add_u32 s8, s38, 0x158080
	s_addc_u32 s9, s39, 0
	s_waitcnt lgkmcnt(0)
	v_lshl_add_u64 v[134:135], s[8:9], 0, v[204:205]
	v_lshl_add_u64 v[136:137], s[8:9], 0, v[206:207]
	s_mov_b32 s11, -2
	s_mov_b64 s[8:9], 0
	s_waitcnt vmcnt(0)
	.p2align	6

.LBB0_1044:
	s_ashr_i32 s29, s28, 31
	s_lshl_b64 s[6:7], s[28:29], 20
	s_add_u32 s44, s57, s6
	s_addc_u32 s45, s58, s7
	s_and_b64 s[6:7], s[36:37], exec
	s_cselect_b32 s9, s45, s49
	s_cselect_b32 s29, s44, s48
	s_ashr_i32 s31, s30, 31
	s_lshl_b64 s[6:7], s[30:31], 20
	s_add_u32 s50, s59, s6
	s_addc_u32 s51, s62, s7
	s_and_b64 s[6:7], s[36:37], exec
	s_cselect_b32 s31, s51, s47
	s_cselect_b32 s34, s50, s46
	s_add_u32 s39, s46, 0x100
	s_addc_u32 s40, s47, 0
	s_add_u32 s6, s48, 0x80080
	v_mov_b32_e32 v2, 0
	s_addc_u32 s7, s49, 0
	s_mov_b32 s41, -2
	v_mov_b32_e32 v3, v2
	v_mov_b32_e32 v4, v2
	v_mov_b32_e32 v5, v2
	v_mov_b32_e32 v6, v2
	v_mov_b32_e32 v7, v2
	s_waitcnt lgkmcnt(0)
	v_mov_b32_e32 v8, v2
	v_mov_b32_e32 v9, v2
	v_mov_b32_e32 v22, v2
	v_mov_b32_e32 v23, v2
	v_mov_b32_e32 v24, v2
	v_mov_b32_e32 v25, v2
	v_mov_b32_e32 v26, v2
	v_mov_b32_e32 v27, v2
	v_mov_b32_e32 v28, v2
	v_mov_b32_e32 v29, v2
	v_mov_b32_e32 v38, v2
	v_mov_b32_e32 v39, v2
	v_mov_b32_e32 v40, v2
	v_mov_b32_e32 v41, v2
	v_mov_b32_e32 v42, v2
	v_mov_b32_e32 v43, v2
	v_mov_b32_e32 v44, v2
	v_mov_b32_e32 v45, v2
	v_mov_b32_e32 v54, v2
	v_mov_b32_e32 v55, v2
	v_mov_b32_e32 v56, v2
	v_mov_b32_e32 v57, v2
	v_mov_b32_e32 v58, v2
	v_mov_b32_e32 v59, v2
	v_mov_b32_e32 v60, v2
	v_mov_b32_e32 v61, v2
	v_mov_b32_e32 v10, v2
	v_mov_b32_e32 v11, v2
	v_mov_b32_e32 v12, v2
	v_mov_b32_e32 v13, v2
	v_mov_b32_e32 v18, v2
	v_mov_b32_e32 v19, v2
	v_mov_b32_e32 v20, v2
	v_mov_b32_e32 v21, v2
	v_mov_b32_e32 v30, v2
	v_mov_b32_e32 v31, v2
	v_mov_b32_e32 v32, v2
	v_mov_b32_e32 v33, v2
	v_mov_b32_e32 v34, v2
	v_mov_b32_e32 v35, v2
	v_mov_b32_e32 v36, v2
	v_mov_b32_e32 v37, v2
	v_mov_b32_e32 v46, v2
	v_mov_b32_e32 v47, v2
	v_mov_b32_e32 v48, v2
	v_mov_b32_e32 v49, v2
	v_mov_b32_e32 v50, v2
	v_mov_b32_e32 v51, v2
	v_mov_b32_e32 v52, v2
	v_mov_b32_e32 v53, v2
	v_mov_b32_e32 v62, v2
	v_mov_b32_e32 v63, v2
	v_mov_b32_e32 v64, v2
	v_mov_b32_e32 v65, v2
	v_mov_b32_e32 v66, v2
	v_mov_b32_e32 v67, v2
	v_mov_b32_e32 v68, v2
	v_mov_b32_e32 v69, v2
	v_mov_b32_e32 v70, v2
	v_mov_b32_e32 v71, v2
	v_mov_b32_e32 v72, v2
	v_mov_b32_e32 v73, v2
	v_mov_b32_e32 v74, v2
	v_mov_b32_e32 v75, v2
	v_mov_b32_e32 v76, v2
	v_mov_b32_e32 v77, v2
	v_mov_b32_e32 v86, v2
	v_mov_b32_e32 v87, v2
	v_mov_b32_e32 v88, v2
	v_mov_b32_e32 v89, v2
	v_mov_b32_e32 v90, v2
	v_mov_b32_e32 v91, v2
	v_mov_b32_e32 v92, v2
	v_mov_b32_e32 v93, v2
	v_mov_b32_e32 v102, v2
	v_mov_b32_e32 v103, v2
	v_mov_b32_e32 v104, v2
	v_mov_b32_e32 v105, v2
	v_mov_b32_e32 v106, v2
	v_mov_b32_e32 v107, v2
	v_mov_b32_e32 v108, v2
	v_mov_b32_e32 v109, v2
	v_mov_b32_e32 v118, v2
	v_mov_b32_e32 v119, v2
	v_mov_b32_e32 v120, v2
	v_mov_b32_e32 v121, v2
	v_mov_b32_e32 v122, v2
	v_mov_b32_e32 v123, v2
	v_mov_b32_e32 v124, v2
	v_mov_b32_e32 v125, v2
	v_mov_b32_e32 v78, v2
	v_mov_b32_e32 v79, v2
	v_mov_b32_e32 v80, v2
	v_mov_b32_e32 v81, v2
	v_mov_b32_e32 v82, v2
	v_mov_b32_e32 v83, v2
	v_mov_b32_e32 v84, v2
	v_mov_b32_e32 v85, v2
	v_mov_b32_e32 v94, v2
	v_mov_b32_e32 v95, v2
	v_mov_b32_e32 v96, v2
	v_mov_b32_e32 v97, v2
	v_mov_b32_e32 v98, v2
	v_mov_b32_e32 v99, v2
	v_mov_b32_e32 v100, v2
	v_mov_b32_e32 v101, v2
	v_mov_b32_e32 v110, v2
	v_mov_b32_e32 v111, v2
	v_mov_b32_e32 v112, v2
	v_mov_b32_e32 v113, v2
	v_mov_b32_e32 v114, v2
	v_mov_b32_e32 v115, v2
	v_mov_b32_e32 v116, v2
	v_mov_b32_e32 v117, v2
	v_mov_b32_e32 v126, v2
	v_mov_b32_e32 v127, v2
	v_mov_b32_e32 v128, v2
	v_mov_b32_e32 v129, v2
	v_mov_b32_e32 v130, v2
	v_mov_b32_e32 v131, v2
	v_mov_b32_e32 v132, v2
	v_mov_b32_e32 v133, v2
	.p2align	6

.LBB0_1299:
	v_lshrrev_b32_e32 v21, 1, v17
	v_and_b32_e32 v81, 24, v21
	v_and_b32_e32 v20, 15, v17
	v_lshlrev_b32_e32 v21, 1, v81
	v_lshl_or_b32 v80, s13, 6, v20
	v_lshl_or_b32 v20, v20, 6, v21
	v_lshlrev_b32_e32 v21, 2, v17
	s_lshl_b32 s13, s13, 13
	v_and_b32_e32 v21, 32, v21
	v_bitop3_b32 v22, v20, s13, v21 bitop3:0xde
	s_lshl_b32 s13, s15, 5
	s_and_b32 s31, s13, 0x60
	s_lshl_b32 s13, s31, 7
	v_bitop3_b32 v82, s13, v20, v21 bitop3:0xf6
	s_mul_i32 s13, s17, 0xa2c0000
	s_mul_hi_u32 s15, s16, 0xa2c0000
	s_add_i32 m0, s25, 0x18000
	v_lshl_add_u64 v[8:9], v[8:9], 0, s[96:97]
	s_add_i32 s15, s15, s13
	s_waitcnt vmcnt(2)
	s_barrier
	global_load_lds_dwordx4 v[8:9], off
	v_lshl_add_u64 v[6:7], v[6:7], 0, s[96:97]
	s_add_i32 m0, s25, 0x1a000
	s_add_i32 s34, s25, 0x8000
	s_add_i32 s36, s25, 0xa000
	global_load_lds_dwordx4 v[6:7], off
	v_lshl_add_u64 v[4:5], v[4:5], 0, s[96:97]
	s_mov_b32 m0, s34
	s_add_u32 s38, s2, 0x100080
	global_load_lds_dwordx4 v[4:5], off
	v_lshl_add_u64 v[2:3], v[2:3], 0, s[96:97]
	s_mov_b32 m0, s36
	s_addc_u32 s39, s3, 0
	s_add_i32 s37, s25, 0x1c000
	global_load_lds_dwordx4 v[2:3], off
	v_lshl_add_u64 v[2:3], s[38:39], 0, v[0:1]
	s_mov_b32 m0, s37
	s_mul_i32 s13, s16, 0xa2c0000
	global_load_lds_dwordx4 v[2:3], off
	v_lshl_add_u64 v[2:3], s[38:39], 0, v[34:35]
	s_add_i32 s38, s25, 0x1e000
	s_mov_b32 m0, s38
	s_add_u32 s12, s12, s13
	global_load_lds_dwordx4 v[2:3], off
	s_addc_u32 s13, 0, s15
	s_add_u32 s12, s8, s12
	s_addc_u32 s13, s9, s13
	s_add_u32 s39, s12, 0x100100
	s_addc_u32 s40, s13, 0
	s_add_u32 s10, s10, s14
	s_addc_u32 s11, s11, 0
	v_lshlrev_b32_e32 v2, 15, v13
	v_and_b32_e32 v2, 0xffff0000, v2
	s_add_u32 s41, s8, s10
	v_lshl_add_u32 v2, v18, 12, v2
	v_and_b32_e32 v3, 1, v13
	s_addc_u32 s44, s9, s11
	v_lshl_or_b32 v2, v3, 6, v2
	s_add_u32 s10, s41, 0x40681080
	v_lshl_add_u32 v2, v19, 1, v2
	v_mov_b32_e32 v3, v1
	s_addc_u32 s11, s44, 0
	v_lshl_add_u64 v[36:37], s[10:11], 0, v[2:3]
	v_lshlrev_b32_e32 v2, 15, v10
	v_and_b32_e32 v2, 0xffff0000, v2
	v_lshl_add_u32 v2, v11, 12, v2
	v_and_b32_e32 v3, 1, v10
	v_lshl_or_b32 v2, v3, 6, v2
	s_waitcnt vmcnt(6)
	v_lshl_add_u32 v2, v12, 1, v2
	v_mov_b32_e32 v3, v1
	v_lshl_add_u64 v[78:79], s[10:11], 0, v[2:3]
	v_mov_b32_e32 v2, 0
	s_mov_b32 s45, -2
	s_mov_b64 s[10:11], 0
	v_add_u32_e32 v83, 0, v22
	v_mov_b32_e32 v3, v2
	v_mov_b32_e32 v4, v2
	v_mov_b32_e32 v5, v2
	v_mov_b32_e32 v6, v2
	v_mov_b32_e32 v7, v2
	v_mov_b32_e32 v8, v2
	v_mov_b32_e32 v9, v2
	v_mov_b32_e32 v10, v2
	v_mov_b32_e32 v11, v2
	v_mov_b32_e32 v12, v2
	v_mov_b32_e32 v13, v2
	v_mov_b32_e32 v18, v2
	v_mov_b32_e32 v19, v2
	v_mov_b32_e32 v20, v2
	v_mov_b32_e32 v21, v2
	v_mov_b32_e32 v22, v2
	v_mov_b32_e32 v23, v2
	v_mov_b32_e32 v24, v2
	v_mov_b32_e32 v25, v2
	v_mov_b32_e32 v26, v2
	v_mov_b32_e32 v27, v2
	v_mov_b32_e32 v28, v2
	v_mov_b32_e32 v29, v2
	v_mov_b32_e32 v38, v2
	v_mov_b32_e32 v39, v2
	v_mov_b32_e32 v40, v2
	v_mov_b32_e32 v41, v2
	v_mov_b32_e32 v42, v2
	v_mov_b32_e32 v43, v2
	v_mov_b32_e32 v44, v2
	v_mov_b32_e32 v45, v2
	v_mov_b32_e32 v46, v2
	v_mov_b32_e32 v47, v2
	v_mov_b32_e32 v48, v2
	v_mov_b32_e32 v49, v2
	v_mov_b32_e32 v50, v2
	v_mov_b32_e32 v51, v2
	v_mov_b32_e32 v52, v2
	v_mov_b32_e32 v53, v2
	v_mov_b32_e32 v54, v2
	v_mov_b32_e32 v55, v2
	v_mov_b32_e32 v56, v2
	v_mov_b32_e32 v57, v2
	v_mov_b32_e32 v58, v2
	v_mov_b32_e32 v59, v2
	v_mov_b32_e32 v60, v2
	v_mov_b32_e32 v61, v2
	v_mov_b32_e32 v62, v2
	v_mov_b32_e32 v63, v2
	v_mov_b32_e32 v64, v2
	v_mov_b32_e32 v65, v2
	v_mov_b32_e32 v66, v2
	v_mov_b32_e32 v67, v2
	v_mov_b32_e32 v68, v2
	v_mov_b32_e32 v69, v2
	v_mov_b32_e32 v70, v2
	v_mov_b32_e32 v71, v2
	v_mov_b32_e32 v72, v2
	v_mov_b32_e32 v73, v2
	v_mov_b32_e32 v74, v2
	v_mov_b32_e32 v75, v2
	v_mov_b32_e32 v76, v2
	v_mov_b32_e32 v77, v2
	s_barrier
	.p2align	6

.LBB0_1320:
	s_ashr_i32 s27, s26, 31
	s_lshl_b64 s[30:31], s[26:27], 18
	s_add_u32 s30, s46, s30
	s_addc_u32 s31, s47, s31
	s_and_b64 s[2:3], s[2:3], exec
	s_cselect_b32 s5, s31, s37
	s_cselect_b32 s7, s30, s36
	s_add_u32 s25, s36, 0x100
	s_addc_u32 s27, s37, 0
	s_add_u32 s2, s38, 0x40080
	v_mov_b32_e32 v2, 0
	s_addc_u32 s3, s39, 0
	s_mov_b32 s34, -2
	v_mov_b32_e32 v3, v2
	v_mov_b32_e32 v4, v2
	v_mov_b32_e32 v5, v2
	v_mov_b32_e32 v6, v2
	v_mov_b32_e32 v7, v2
	v_mov_b32_e32 v8, v2
	v_mov_b32_e32 v9, v2
	v_mov_b32_e32 v22, v2
	v_mov_b32_e32 v23, v2
	v_mov_b32_e32 v24, v2
	v_mov_b32_e32 v25, v2
	v_mov_b32_e32 v26, v2
	v_mov_b32_e32 v27, v2
	v_mov_b32_e32 v28, v2
	v_mov_b32_e32 v29, v2
	v_mov_b32_e32 v38, v2
	v_mov_b32_e32 v39, v2
	v_mov_b32_e32 v40, v2
	v_mov_b32_e32 v41, v2
	v_mov_b32_e32 v42, v2
	v_mov_b32_e32 v43, v2
	v_mov_b32_e32 v44, v2
	v_mov_b32_e32 v45, v2
	v_mov_b32_e32 v54, v2
	v_mov_b32_e32 v55, v2
	v_mov_b32_e32 v56, v2
	v_mov_b32_e32 v57, v2
	v_mov_b32_e32 v58, v2
	v_mov_b32_e32 v59, v2
	v_mov_b32_e32 v60, v2
	v_mov_b32_e32 v61, v2
	v_mov_b32_e32 v10, v2
	v_mov_b32_e32 v11, v2
	v_mov_b32_e32 v12, v2
	v_mov_b32_e32 v13, v2
	v_mov_b32_e32 v18, v2
	v_mov_b32_e32 v19, v2
	v_mov_b32_e32 v20, v2
	v_mov_b32_e32 v21, v2
	v_mov_b32_e32 v30, v2
	v_mov_b32_e32 v31, v2
	v_mov_b32_e32 v32, v2
	v_mov_b32_e32 v33, v2
	v_mov_b32_e32 v34, v2
	v_mov_b32_e32 v35, v2
	v_mov_b32_e32 v36, v2
	v_mov_b32_e32 v37, v2
	v_mov_b32_e32 v46, v2
	v_mov_b32_e32 v47, v2
	v_mov_b32_e32 v48, v2
	v_mov_b32_e32 v49, v2
	v_mov_b32_e32 v50, v2
	v_mov_b32_e32 v51, v2
	v_mov_b32_e32 v52, v2
	v_mov_b32_e32 v53, v2
	v_mov_b32_e32 v62, v2
	v_mov_b32_e32 v63, v2
	v_mov_b32_e32 v64, v2
	v_mov_b32_e32 v65, v2
	v_mov_b32_e32 v66, v2
	v_mov_b32_e32 v67, v2
	v_mov_b32_e32 v68, v2
	v_mov_b32_e32 v69, v2
	v_mov_b32_e32 v70, v2
	v_mov_b32_e32 v71, v2
	v_mov_b32_e32 v72, v2
	v_mov_b32_e32 v73, v2
	v_mov_b32_e32 v74, v2
	v_mov_b32_e32 v75, v2
	v_mov_b32_e32 v76, v2
	v_mov_b32_e32 v77, v2
	v_mov_b32_e32 v86, v2
	v_mov_b32_e32 v87, v2
	v_mov_b32_e32 v88, v2
	v_mov_b32_e32 v89, v2
	v_mov_b32_e32 v90, v2
	v_mov_b32_e32 v91, v2
	v_mov_b32_e32 v92, v2
	v_mov_b32_e32 v93, v2
	v_mov_b32_e32 v102, v2
	v_mov_b32_e32 v103, v2
	v_mov_b32_e32 v104, v2
	v_mov_b32_e32 v105, v2
	v_mov_b32_e32 v106, v2
	v_mov_b32_e32 v107, v2
	v_mov_b32_e32 v108, v2
	v_mov_b32_e32 v109, v2
	v_mov_b32_e32 v118, v2
	v_mov_b32_e32 v119, v2
	v_mov_b32_e32 v120, v2
	v_mov_b32_e32 v121, v2
	v_mov_b32_e32 v122, v2
	v_mov_b32_e32 v123, v2
	v_mov_b32_e32 v124, v2
	v_mov_b32_e32 v125, v2
	v_mov_b32_e32 v78, v2
	v_mov_b32_e32 v79, v2
	v_mov_b32_e32 v80, v2
	v_mov_b32_e32 v81, v2
	v_mov_b32_e32 v82, v2
	v_mov_b32_e32 v83, v2
	v_mov_b32_e32 v84, v2
	v_mov_b32_e32 v85, v2
	v_mov_b32_e32 v94, v2
	v_mov_b32_e32 v95, v2
	v_mov_b32_e32 v96, v2
	v_mov_b32_e32 v97, v2
	v_mov_b32_e32 v98, v2
	v_mov_b32_e32 v99, v2
	v_mov_b32_e32 v100, v2
	v_mov_b32_e32 v101, v2
	v_mov_b32_e32 v110, v2
	v_mov_b32_e32 v111, v2
	v_mov_b32_e32 v112, v2
	v_mov_b32_e32 v113, v2
	v_mov_b32_e32 v114, v2
	v_mov_b32_e32 v115, v2
	v_mov_b32_e32 v116, v2
	v_mov_b32_e32 v117, v2
	v_mov_b32_e32 v126, v2
	v_mov_b32_e32 v127, v2
	v_mov_b32_e32 v128, v2
	v_mov_b32_e32 v129, v2
	v_mov_b32_e32 v130, v2
	v_mov_b32_e32 v131, v2
	v_mov_b32_e32 v132, v2
	v_mov_b32_e32 v133, v2
	.p2align	6

.LBB0_2398:
	s_xor_b64 s[28:29], s[38:39], -1
	s_add_u32 s63, s44, 0x100
	s_addc_u32 s64, s45, 0
	s_ashr_i32 s25, s24, 31
	s_lshl_b64 s[30:31], s[24:25], 20
	s_add_u32 s36, s49, s30
	s_addc_u32 s37, s50, s31
	s_and_b64 s[30:31], s[38:39], exec
	s_cselect_b32 s25, s37, s23
	s_cselect_b32 s34, s36, s22
	s_ashr_i32 s27, s26, 31
	s_lshl_b64 s[30:31], s[26:27], 20
	s_add_u32 s30, s51, s30
	s_addc_u32 s31, s52, s31
	s_and_b64 s[46:47], s[38:39], exec
	s_cselect_b32 s27, s31, s45
	s_cselect_b32 s65, s30, s44
	s_add_u32 s44, s22, 0x80080
	s_addc_u32 s45, s23, 0
	s_waitcnt lgkmcnt(0)
	v_lshl_add_u64 v[138:139], s[44:45], 0, v[134:135]
	v_lshl_add_u64 v[140:141], s[44:45], 0, v[136:137]
	s_mov_b32 s66, -2
	.p2align	6
